# seams after P1 / chunk GEMM / attention: no L2 write-back (all stores of those phases are device-scope write-through)
# baseline (speedup 1.0000x reference)
.LBB0_230:
	s_or_b64 exec, exec, s[10:11]
	v_cvt_f32_u32_e32 v6, v4
	s_waitcnt vmcnt(0)
	v_readfirstlane_b32 s8, v5
	v_sub_u32_e32 v5, 0, v4
	v_rcp_iflag_f32_e32 v6, v6
	v_add_u32_e32 v7, s8, v3
	v_mul_f32_e32 v6, 0x4f7ffffe, v6
	v_cvt_u32_f32_e32 v6, v6
	v_mul_lo_u32 v3, v5, v6
	v_mul_hi_u32 v3, v6, v3
	v_add_u32_e32 v3, v6, v3
	v_mul_hi_u32 v3, v7, v3
	v_mul_lo_u32 v5, v3, v4
	v_sub_u32_e32 v5, v7, v5
	v_add_u32_e32 v6, 1, v3
	v_cmp_ge_u32_e32 vcc, v5, v4
	s_nop 1
	v_cndmask_b32_e32 v3, v3, v6, vcc
	v_sub_u32_e32 v6, v5, v4
	v_cndmask_b32_e32 v5, v5, v6, vcc
	v_add_u32_e32 v6, 1, v3
	v_cmp_ge_u32_e32 vcc, v5, v4
	v_add_u32_e32 v5, 1, v7
	s_nop 0
	v_cndmask_b32_e32 v3, v3, v6, vcc
	v_mul_lo_u32 v6, v4, v3
	v_add_u32_e32 v4, v6, v4
	v_cmp_ne_u32_e32 vcc, v5, v4
	s_cbranch_vccnz .Lsm1_poll
	s_nop 0
	s_waitcnt vmcnt(0) lgkmcnt(0)
	v_mov_b32_e32 v5, 0x1e03000
	v_mov_b32_e32 v6, 1
	global_atomic_add v5, v6, s[40:41] offset:1024

.LBB0_1082:
	s_or_b64 exec, exec, s[6:7]
	v_cvt_f32_u32_e32 v4, v2
	s_waitcnt vmcnt(0)
	v_readfirstlane_b32 s6, v3
	v_sub_u32_e32 v3, 0, v2
	v_rcp_iflag_f32_e32 v4, v4
	v_add_u32_e32 v5, s6, v1
	v_mul_f32_e32 v4, 0x4f7ffffe, v4
	v_cvt_u32_f32_e32 v4, v4
	v_mul_lo_u32 v1, v3, v4
	v_mul_hi_u32 v1, v4, v1
	v_add_u32_e32 v1, v4, v1
	v_mul_hi_u32 v1, v5, v1
	v_mul_lo_u32 v3, v1, v2
	v_sub_u32_e32 v3, v5, v3
	v_add_u32_e32 v4, 1, v1
	v_cmp_ge_u32_e32 vcc, v3, v2
	s_nop 1
	v_cndmask_b32_e32 v1, v1, v4, vcc
	v_sub_u32_e32 v4, v3, v2
	v_cndmask_b32_e32 v3, v3, v4, vcc
	v_add_u32_e32 v4, 1, v1
	v_cmp_ge_u32_e32 vcc, v3, v2
	v_add_u32_e32 v3, 1, v5
	s_nop 0
	v_cndmask_b32_e32 v1, v1, v4, vcc
	v_mul_lo_u32 v4, v2, v1
	v_add_u32_e32 v2, v4, v2
	v_cmp_ne_u32_e32 vcc, v3, v2
	s_cbranch_vccnz .Lsm6_poll
	s_nop 0
	s_waitcnt vmcnt(0) lgkmcnt(0)
	v_readlane_b32 s98, v253, 43
	v_readlane_b32 s99, v253, 44
	v_mov_b32_e32 v4, 1
	s_nop 4
	global_atomic_add v139, v4, s[98:99]

.LBB0_1179:
	global_store_dword v[92:93], v100, off sc1

.LBB0_1461:
	s_or_b64 exec, exec, s[4:5]
	v_cvt_f32_u32_e32 v4, v2
	s_waitcnt vmcnt(0)
	v_readfirstlane_b32 s4, v3
	v_sub_u32_e32 v3, 0, v2
	v_rcp_iflag_f32_e32 v4, v4
	v_add_u32_e32 v5, s4, v1
	v_mul_f32_e32 v4, 0x4f7ffffe, v4
	v_cvt_u32_f32_e32 v4, v4
	v_mul_lo_u32 v1, v3, v4
	v_mul_hi_u32 v1, v4, v1
	v_add_u32_e32 v1, v4, v1
	v_mul_hi_u32 v1, v5, v1
	v_mul_lo_u32 v3, v1, v2
	v_sub_u32_e32 v3, v5, v3
	v_add_u32_e32 v4, 1, v1
	v_cmp_ge_u32_e32 vcc, v3, v2
	s_nop 1
	v_cndmask_b32_e32 v1, v1, v4, vcc
	v_sub_u32_e32 v4, v3, v2
	v_cndmask_b32_e32 v3, v3, v4, vcc
	v_add_u32_e32 v4, 1, v1
	v_cmp_ge_u32_e32 vcc, v3, v2
	v_add_u32_e32 v3, 1, v5
	s_nop 0
	v_cndmask_b32_e32 v1, v1, v4, vcc
	v_mul_lo_u32 v4, v2, v1
	v_add_u32_e32 v2, v4, v2
	v_cmp_ne_u32_e32 vcc, v3, v2
	s_cbranch_vccnz .Lsm7_poll
	s_nop 0
	s_waitcnt vmcnt(0) lgkmcnt(0)
	v_readlane_b32 s98, v253, 43
	v_readlane_b32 s99, v253, 44
	v_mov_b32_e32 v4, 1
	s_nop 4
	global_atomic_add v139, v4, s[98:99]
